# top-k (second query copy): exact-count exit of the threshold search goes straight to scan+compaction, skipping the separate counting pass
# baseline (speedup 1.0000x reference)
.LBB0_2738:
	v_mov_b32_e32 v77, v37
	s_nop 1
	v_add_u32_dpp v37, v37, v37 quad_perm:[1,0,3,2] row_mask:0xf bank_mask:0xf bound_ctrl:1
	s_nop 1
	v_add_u32_dpp v37, v37, v37 quad_perm:[2,3,0,1] row_mask:0xf bank_mask:0xf bound_ctrl:1
	s_nop 1
	v_add_u32_dpp v37, v37, v37 row_half_mirror row_mask:0xf bank_mask:0xf bound_ctrl:1
	s_nop 1
	v_add_u32_dpp v37, v37, v37 row_mirror row_mask:0xf bank_mask:0xf bound_ctrl:1
	s_nop 1
	v_add_u32_dpp v37, v37, v37 row_bcast:15 row_mask:0xa bank_mask:0xf
	s_nop 1
	v_add_u32_dpp v37, v37, v37 row_bcast:31 row_mask:0xc bank_mask:0xf
	s_nop 0
	v_readlane_b32 s16, v37, 63
	s_cmpk_gt_i32 s16, 0xff
	s_cselect_b64 s[2:3], -1, 0
	s_and_b64 s[0:1], s[2:3], exec
	s_cselect_b32 s18, s8, s18
	s_cmpk_eq_i32 s16, 0x100
	s_mov_b64 s[0:1], -1
	s_cbranch_scc1 .Lsel_fast_c2
	s_and_b64 s[0:1], s[2:3], exec
	s_cselect_b32 s4, s4, s8
	s_cselect_b32 s5, s16, s5
	s_cselect_b32 s6, s6, s16
	s_add_i32 s7, s7, 1
	s_sub_i32 s9, s4, s18
	s_cmp_lt_u32 s9, 2
	s_cselect_b64 s[0:1], -1, 0
	s_branch .LBB0_2729

.LBB0_2878:
	s_or_b64 exec, exec, s[4:5]
	s_branch .LBB0_2879
.Lsel_fast_c2:
	v_mov_b32_e32 v84, v77
	v_mov_b32_e32 v76, 0
	s_mov_b64 s[42:43], -1
	s_branch .LBB0_2880
